# as v33 plus MLA loop head: K/V address and DMA slot SALU moved in front of the per-tile barrier
# speedup vs baseline: 1.0008x; 1.0008x over previous
; #define ATT_DMA(t, sk, sv) do { glds16(ksrc + (long)(t) * 64 * a.ldk, (unsigned)__builtin_amdgcn_readfirstlane(kdst + (sk) * KSLOT)); \
;         if (MODE == 0 && wid < 4) glds16(kpsrc + (long)(t) * 64 * 32, (unsigned)__builtin_amdgcn_readfirstlane(kpdst + (sk) * KSLOT)); \
;         glds16(vsrc + (long)(t) * 64 * a.ldv, (unsigned)__builtin_amdgcn_readfirstlane(vdst + (sv) * VSLOT)); } while (0)
; #define ATT_WAIT_BAR() asm volatile("s_waitcnt vmcnt(0) lgkmcnt(0)\n\ts_barrier" ::: "memory")
; template <int MODE> __device__ __forceinline__ void attn_unit(const Unit& a, char* shm) {
;     ...
;     for (int t = a.t_lo; t < a.t_hi; ++t) {
;         const int s = (t - a.t_lo) & 1;
;         ATT_WAIT_BAR();
;         if (t + 1 < a.t_hi) ATT_DMA(t + 1, s ^ 1, (sv == 2 ? 0 : sv + 1));
;         if (pend) { ATT_PV(pw, svp); pend = false; }
;         bool active = true;
;         if (MODE == 1) active = (64 * t + 63 >= tq0 - 128) && (64 * t <= tq0 + 31 + 128);
;         if (active) {
;             const lds_cptr kp = shm3 + LDS_K + s * KSLOT + hi * 1024 + r32 * 16;
;     ...
;             if (g == 0) ATT_PV(pw, sv); else pend = true;
;         }
;         svp = sv; sv = (sv == 2) ? 0 : sv + 1;
.LBB0_1910:
	s_add_i32 s50, s50, 1
	s_mov_b32 s51, s0
	s_mov_b32 s34, s51
	s_mulk_i32 s34, 0x3000
	s_cmp_eq_u32 s51, 2
	s_cselect_b32 s34, 0x14800, s34
	v_add_u32_e32 v118, s34, v146
	v_lshl_add_u32 v149, s51, 13, v147
	s_mov_b32 s12, m0
	s_add_i32 s35, s51, -1
	s_cmp_eq_u32 s51, 0
	s_cselect_b32 s35, 2, s35
	s_mul_i32 s0, s35, 0x3000
	s_cmp_eq_u32 s35, 2
	s_cselect_b32 s0, 0x14800, s0
	s_and_b64 vcc, exec, s[40:41]
	s_cbranch_vccnz .Lmla_w2
	s_waitcnt vmcnt(2) lgkmcnt(0)
	s_branch .Lmla_wd

; #define LAS __attribute__((address_space(3)))
; template <int MODE> __device__ __forceinline__ void attn_unit(const Unit& a, char* shm) {
;     ...
;         if (pend) { ATT_PV(pw, svp); pend = false; }
;         bool active = true;
;         if (MODE == 1) active = (64 * t + 63 >= tq0 - 128) && (64 * t <= tq0 + 31 + 128);
;         if (active) {
;             const lds_cptr kp = shm3 + LDS_K + s * KSLOT + hi * 1024 + r32 * 16;
;             f32x16 p0 = negm, p1 = negm;
; #pragma unroll
;             for (int d0 = 0; d0 < ND; ++d0) {
;                 const bf16x8 b0 = *(const LAS bf16x8*)(kp + d0 * 2048), b1 = *(const LAS bf16x8*)(kp + d0 * 2048 + 512);
.Lmla_wd:
	s_barrier
	ds_read_b128 v[182:185], v118
	ds_read_b128 v[186:189], v118 offset:512
	ds_read_b128 v[190:193], v118 offset:2048
	ds_read_b128 v[194:197], v118 offset:2560
	ds_read_b128 v[198:201], v118 offset:4096
	ds_read_b128 v[202:205], v118 offset:4608
	ds_read_b128 v[206:209], v118 offset:6144
	ds_read_b128 v[210:213], v118 offset:6656
	ds_read_b128 v[214:217], v118 offset:8192
	ds_read_b128 v[218:221], v118 offset:8704
	ds_read_b128 v[222:225], v118 offset:10240
	ds_read_b128 v[226:229], v118 offset:10752
	s_andn2_b64 vcc, exec, s[2:3]
	s_cbranch_vccnz .Lmla_aprio
	v_mfma_f32_32x32x16_bf16 v[0:15], v[60:63], v[230:233], v[0:15]
	v_mfma_f32_32x32x16_bf16 v[0:15], v[56:59], v[234:237], v[0:15]
	v_mfma_f32_32x32x16_bf16 v[0:15], v[52:55], v[238:241], v[0:15]
	v_mfma_f32_32x32x16_bf16 v[0:15], v[48:51], v[242:245], v[0:15]
	v_mfma_f32_32x32x16_bf16 v[16:31], v[60:63], v[246:249], v[16:31]
	v_mfma_f32_32x32x16_bf16 v[16:31], v[56:59], v[150:153], v[16:31]
	v_mfma_f32_32x32x16_bf16 v[16:31], v[52:55], v[154:157], v[16:31]
	v_mfma_f32_32x32x16_bf16 v[16:31], v[48:51], v[158:161], v[16:31]
	s_branch .LBB0_1916
